# row-max rewrite extended to the eighth cluster (all attention softmax row maxima are 16-instruction v_max3 chains)
# baseline (speedup 1.0000x reference)
.LBB0_167:
	v_add_f32_e32 v32, v48, v32
	v_add_f32_e32 v32, 0, v32
	v_add_f32_e32 v33, v49, v33
	v_add_f32_e32 v32, v33, v32
	v_add_f32_e32 v33, v50, v34
	v_add_f32_e32 v32, v33, v32
	v_add_f32_e32 v33, v51, v35
	v_add_f32_e32 v32, v33, v32
	v_add_f32_e32 v33, v52, v36
	v_add_f32_e32 v32, v33, v32
	v_add_f32_e32 v33, v53, v37
	v_add_f32_e32 v32, v33, v32
	v_add_f32_e32 v33, v54, v38
	v_add_f32_e32 v32, v33, v32
	v_add_f32_e32 v33, v55, v39
	v_add_f32_e32 v32, v33, v32
	v_add_f32_e32 v33, v56, v40
	v_add_f32_e32 v32, v33, v32
	v_add_f32_e32 v33, v57, v41
	v_add_f32_e32 v32, v33, v32
	v_add_f32_e32 v33, v58, v42
	v_add_f32_e32 v32, v33, v32
	v_add_f32_e32 v33, v59, v43
	v_add_f32_e32 v32, v33, v32
	v_add_f32_e32 v33, v60, v44
	v_add_f32_e32 v32, v33, v32
	v_add_f32_e32 v33, v61, v45
	v_add_f32_e32 v32, v33, v32
	v_add_f32_e32 v33, v62, v46
	v_add_f32_e32 v32, v33, v32
	v_add_f32_e32 v33, v63, v47
	v_add_f32_e32 v32, v33, v32
	v_add_f32_e32 v96, v121, v32
	ds_read_b128 v[32:35], v115 offset:23040
	ds_read_b128 v[36:39], v115 offset:18432
	ds_read_b128 v[98:101], v115 offset:18464
	ds_read_b128 v[102:105], v115 offset:23072
	ds_read_b128 v[106:109], v115 offset:18496
	ds_read_b128 v[110:113], v115 offset:23104
	ds_read_b128 v[124:127], v115 offset:18528
	ds_read_b128 v[128:131], v115 offset:23136
	s_setprio 1
	s_setprio 0
	s_waitcnt lgkmcnt(6)
	v_mfma_f32_32x32x16_bf16 v[48:63], v[36:39], v[64:67], 0
	v_mfma_f32_32x32x16_bf16 v[32:47], v[32:35], v[64:67], 0
	s_waitcnt lgkmcnt(5)
	v_mfma_f32_32x32x16_bf16 v[48:63], v[98:101], v[68:71], v[48:63]
	s_waitcnt lgkmcnt(4)
	v_mfma_f32_32x32x16_bf16 v[32:47], v[102:105], v[68:71], v[32:47]
	s_waitcnt lgkmcnt(3)
	v_mfma_f32_32x32x16_bf16 v[48:63], v[106:109], v[72:75], v[48:63]
	s_waitcnt lgkmcnt(2)
	v_mfma_f32_32x32x16_bf16 v[32:47], v[110:113], v[72:75], v[32:47]
	ds_read_b128 v[110:113], v119 offset:27648
	ds_read_b128 v[106:109], v119 offset:27680
	ds_read_b128 v[102:105], v119 offset:27712
	ds_read_b128 v[98:101], v119 offset:27744
	s_waitcnt lgkmcnt(5)
	v_mfma_f32_32x32x16_bf16 v[48:63], v[124:127], v[76:79], v[48:63]
	s_waitcnt lgkmcnt(4)
	v_mfma_f32_32x32x16_bf16 v[32:47], v[128:131], v[76:79], v[32:47]
	s_nop 11
	v_max3_f32 v120, v32, v33, v34
	v_max3_f32 v120, v120, v35, v36
	v_max3_f32 v120, v120, v37, v38
	v_max3_f32 v120, v120, v39, v40
	v_max3_f32 v120, v120, v41, v42
	v_max3_f32 v120, v120, v43, v44
	v_max3_f32 v120, v120, v45, v46
	v_max3_f32 v120, v120, v47, v48
	v_max3_f32 v120, v120, v49, v50
	v_max3_f32 v120, v120, v51, v52
	v_max3_f32 v120, v120, v53, v54
	v_max3_f32 v120, v120, v55, v56
	v_max3_f32 v120, v120, v57, v58
	v_max3_f32 v120, v120, v59, v60
	v_max3_f32 v120, v120, v61, v62
	v_max_f32_e32 v120, v120, v63
	v_mov_b32_e32 v121, v120
	s_nop 1
	v_permlane32_swap_b32_e32 v120, v121
	v_max3_f32 v120, v122, v120, v121
	v_add_f32_e32 v121, 0x41000000, v122
	v_cmp_gt_f32_e32 vcc, v120, v121
	s_cbranch_vccz .LBB0_169
	v_sub_f32_e32 v121, v122, v120
	v_exp_f32_e32 v122, v121
	s_nop 0
	v_mul_f32_e32 v96, v96, v122
	v_pk_mul_f32 v[14:15], v[14:15], v[122:123] op_sel_hi:[1,0]
	v_pk_mul_f32 v[12:13], v[12:13], v[122:123] op_sel_hi:[1,0]
	v_pk_mul_f32 v[10:11], v[10:11], v[122:123] op_sel_hi:[1,0]
	v_pk_mul_f32 v[8:9], v[8:9], v[122:123] op_sel_hi:[1,0]
	v_pk_mul_f32 v[6:7], v[6:7], v[122:123] op_sel_hi:[1,0]
	v_pk_mul_f32 v[4:5], v[4:5], v[122:123] op_sel_hi:[1,0]
	v_pk_mul_f32 v[2:3], v[2:3], v[122:123] op_sel_hi:[1,0]
	v_pk_mul_f32 v[0:1], v[0:1], v[122:123] op_sel_hi:[1,0]
	v_pk_mul_f32 v[30:31], v[30:31], v[122:123] op_sel_hi:[1,0]
	v_pk_mul_f32 v[28:29], v[28:29], v[122:123] op_sel_hi:[1,0]
	v_pk_mul_f32 v[26:27], v[26:27], v[122:123] op_sel_hi:[1,0]
	v_pk_mul_f32 v[24:25], v[24:25], v[122:123] op_sel_hi:[1,0]
	v_pk_mul_f32 v[22:23], v[22:23], v[122:123] op_sel_hi:[1,0]
	v_pk_mul_f32 v[20:21], v[20:21], v[122:123] op_sel_hi:[1,0]
	v_pk_mul_f32 v[18:19], v[18:19], v[122:123] op_sel_hi:[1,0]
	v_pk_mul_f32 v[16:17], v[16:17], v[122:123] op_sel_hi:[1,0]
	s_branch .LBB0_170
